# DSA item prologue: bias-table loop unrolled with its 4 loads batched; phase-0 w_in transpose loads batched
# baseline (speedup 1.0000x reference)
; template <int MODE, bool FAST>
; DI void attn_item(const Params& p, int layer, int b, int hd, int qt, char* smem) {
;     ...
;     tq = qt * 16 + wave * 4 + (r >> 3); hdl = r & 7; wmin = qt * 16 + wave * 4; wmax = wmin + 3; nt64 = (qt >> 2) + 1;
;     qrow = (const u16*)(p.ws + WS_DSQ) + ((size_t)(tokbase + tq) * 8 + hdl) * 64;
;     kbase = (const u16*)(p.ws + WS_DSK) + (size_t)tokbase * 64; kstride = 64;
;     vbase = (const u16*)(p.ws + WS_VTC) + (size_t)(b * 64) * 4096;
;   }
;   int posq = 0, wposmin = 0;
;   if (MODE == 2) {
;     posq = p.pos[tokbase + tq];
;     wposmin = posq;
; #pragma unroll
;     for (int off = 1; off < 64; off <<= 1) { const int o = __shfl_xor(wposmin, off); wposmin = wposmin < o ? wposmin : o; }
;     wposmin = __builtin_amdgcn_readfirstlane(wposmin);
;     for (int e = tid; e < 1024; e += 256) {
.LBB0_202:
	s_and_b64 vcc, exec, s[36:37]
	s_cbranch_vccz .LBB0_208
	v_mov_b32_e32 v4, v128
	s_movk_i32 s10, 0x400
	v_readfirstlane_b32 s6, v4
	s_ashr_i32 s6, s6, 4
	s_and_b32 s6, s6, -4
	v_bfe_u32 v5, v4, 3, 2
	s_add_i32 s54, s6, s30
	v_or_b32_e32 v0, s12, v5
	v_add_u32_e32 v150, s54, v0
	v_ashrrev_i32_e32 v151, 31, v150
	v_lshl_add_u64 v[0:1], v[150:151], 2, s[62:63]
	global_load_dword v186, v[0:1], off
	v_and_b32_e32 v169, 7, v4
	v_cmp_gt_i32_e32 vcc, s10, v4
	v_lshlrev_b32_e32 v187, 2, v169
	s_waitcnt vmcnt(0)
	ds_bpermute_b32 v0, v180, v186
	s_waitcnt lgkmcnt(0)
	v_min_i32_e32 v0, v186, v0
	ds_bpermute_b32 v1, v181, v0
	s_waitcnt lgkmcnt(0)
	v_min_i32_e32 v0, v0, v1
	ds_bpermute_b32 v1, v182, v0
	s_waitcnt lgkmcnt(0)
	v_min_i32_e32 v0, v0, v1
	ds_bpermute_b32 v1, v183, v0
	s_waitcnt lgkmcnt(0)
	v_min_i32_e32 v0, v0, v1
	ds_bpermute_b32 v1, v184, v0
	s_waitcnt lgkmcnt(0)
	v_min_i32_e32 v0, v0, v1
	ds_bpermute_b32 v1, v185, v0
	s_waitcnt lgkmcnt(0)
	v_min_i32_e32 v0, v0, v1
	s_nop 0
	v_readfirstlane_b32 s56, v0
	s_and_saveexec_b64 s[36:37], vcc
	s_cbranch_execz .LBB0_209
; template <int MODE, bool FAST>
; DI void attn_item(const Params& p, int layer, int b, int hd, int qt, char* smem) {
;     ...
;     for (int e = tid; e < 1024; e += 256) {
;       const int n = e >> 3, hh = e & 7;
;       int bk = n;
;       if (n >= 16) {
;         bk = 16 + (n >= 19) + (n >= 21) + (n >= 24) + (n >= 27) + (n >= 31) + (n >= 35) + (n >= 40) + (n >= 46) + (n >= 52) + (n >= 59) + (n >= 67) + (n >= 77) + (n >= 87) + (n >= 99) + (n >= 113);
;       }
;       sBias[e] = (p.rel_bias[bk * 8 + hh] - p.rel_bias[31 * 8 + hh]) * LOG2E;
;     }
	global_load_dword v0, v187, s[84:85] offset:992
	v_lshl_add_u32 v1, v4, 2, v209
	v_ashrrev_i32_e32 v6, 3, v4
	v_mov_b32_e32 v9, v6
	v_cmp_lt_u32_e32 vcc, 18, v6
	s_movk_i32 s10, 0x42
	s_nop 0
	v_cndmask_b32_e64 v7, 16, 17, vcc
	v_cmp_lt_u32_e32 vcc, 20, v6
	s_nop 1
	v_cndmask_b32_e64 v8, 0, 1, vcc
	v_cmp_lt_u32_e32 vcc, 23, v6
	s_nop 1
	v_addc_co_u32_e32 v7, vcc, v7, v8, vcc
	v_cmp_lt_u32_e32 vcc, 26, v6
	s_nop 1
	v_cndmask_b32_e64 v8, 0, 1, vcc
	v_cmp_lt_u32_e32 vcc, 30, v6
	s_nop 1
	v_addc_co_u32_e32 v7, vcc, v7, v8, vcc
	v_cmp_lt_u32_e32 vcc, 34, v6
	s_nop 1
	v_cndmask_b32_e64 v8, 0, 1, vcc
	v_cmp_lt_u32_e32 vcc, 39, v6
	s_nop 1
	v_addc_co_u32_e32 v7, vcc, v7, v8, vcc
	v_cmp_lt_u32_e32 vcc, 45, v6
	s_nop 1
	v_cndmask_b32_e64 v8, 0, 1, vcc
	v_cmp_lt_u32_e32 vcc, 51, v6
	s_nop 1
	v_addc_co_u32_e32 v7, vcc, v7, v8, vcc
	v_cmp_lt_u32_e32 vcc, 58, v6
	s_nop 1
	v_cndmask_b32_e64 v8, 0, 1, vcc
	v_cmp_lt_u32_e32 vcc, s10, v6
	s_movk_i32 s10, 0x4c
	s_nop 0
	v_addc_co_u32_e32 v7, vcc, v7, v8, vcc
	v_cmp_lt_u32_e32 vcc, s10, v6
	s_movk_i32 s10, 0x56
	s_nop 0
	v_cndmask_b32_e64 v8, 0, 1, vcc
	v_cmp_lt_u32_e32 vcc, s10, v6
	s_movk_i32 s10, 0x62
	s_nop 0
	v_addc_co_u32_e32 v7, vcc, v7, v8, vcc
	v_cmp_lt_u32_e32 vcc, s10, v6
	s_nop 1
	v_cndmask_b32_e64 v8, 0, 1, vcc
	v_cmp_lt_u32_e32 vcc, s57, v6
	s_nop 1
	v_addc_co_u32_e32 v6, vcc, v7, v8, vcc
	v_cmp_lt_i32_e32 vcc, 15, v9
	s_nop 1
	v_cndmask_b32_e32 v6, v9, v6, vcc
	v_lshl_or_b32 v6, v6, 3, v169
	v_ashrrev_i32_e32 v7, 31, v6
	v_lshl_add_u64 v[6:7], v[6:7], 2, s[84:85]
	global_load_dword v14, v[6:7], off
	v_add_u32_e32 v2, 0x100, v4
	v_ashrrev_i32_e32 v6, 3, v2
	v_mov_b32_e32 v9, v6
	v_cmp_lt_u32_e32 vcc, 18, v6
	s_movk_i32 s10, 0x42
	s_nop 0
	v_cndmask_b32_e64 v7, 16, 17, vcc
	v_cmp_lt_u32_e32 vcc, 20, v6
	s_nop 1
	v_cndmask_b32_e64 v8, 0, 1, vcc
	v_cmp_lt_u32_e32 vcc, 23, v6
	s_nop 1
	v_addc_co_u32_e32 v7, vcc, v7, v8, vcc
	v_cmp_lt_u32_e32 vcc, 26, v6
	s_nop 1
	v_cndmask_b32_e64 v8, 0, 1, vcc
	v_cmp_lt_u32_e32 vcc, 30, v6
	s_nop 1
	v_addc_co_u32_e32 v7, vcc, v7, v8, vcc
	v_cmp_lt_u32_e32 vcc, 34, v6
	s_nop 1
	v_cndmask_b32_e64 v8, 0, 1, vcc
	v_cmp_lt_u32_e32 vcc, 39, v6
	s_nop 1
	v_addc_co_u32_e32 v7, vcc, v7, v8, vcc
	v_cmp_lt_u32_e32 vcc, 45, v6
	s_nop 1
	v_cndmask_b32_e64 v8, 0, 1, vcc
	v_cmp_lt_u32_e32 vcc, 51, v6
	s_nop 1
	v_addc_co_u32_e32 v7, vcc, v7, v8, vcc
	v_cmp_lt_u32_e32 vcc, 58, v6
	s_nop 1
	v_cndmask_b32_e64 v8, 0, 1, vcc
	v_cmp_lt_u32_e32 vcc, s10, v6
	s_movk_i32 s10, 0x4c
	s_nop 0
	v_addc_co_u32_e32 v7, vcc, v7, v8, vcc
	v_cmp_lt_u32_e32 vcc, s10, v6
	s_movk_i32 s10, 0x56
	s_nop 0
	v_cndmask_b32_e64 v8, 0, 1, vcc
	v_cmp_lt_u32_e32 vcc, s10, v6
	s_movk_i32 s10, 0x62
	s_nop 0
	v_addc_co_u32_e32 v7, vcc, v7, v8, vcc
	v_cmp_lt_u32_e32 vcc, s10, v6
	s_nop 1
	v_cndmask_b32_e64 v8, 0, 1, vcc
	v_cmp_lt_u32_e32 vcc, s57, v6
	s_nop 1
	v_addc_co_u32_e32 v6, vcc, v7, v8, vcc
	v_cmp_lt_i32_e32 vcc, 15, v9
	s_nop 1
	v_cndmask_b32_e32 v6, v9, v6, vcc
	v_lshl_or_b32 v6, v6, 3, v169
	v_ashrrev_i32_e32 v7, 31, v6
	v_lshl_add_u64 v[6:7], v[6:7], 2, s[84:85]
	global_load_dword v15, v[6:7], off
	v_add_u32_e32 v2, 0x200, v4
	v_ashrrev_i32_e32 v6, 3, v2
	v_mov_b32_e32 v9, v6
	v_cmp_lt_u32_e32 vcc, 18, v6
	s_movk_i32 s10, 0x42
	s_nop 0
	v_cndmask_b32_e64 v7, 16, 17, vcc
	v_cmp_lt_u32_e32 vcc, 20, v6
	s_nop 1
	v_cndmask_b32_e64 v8, 0, 1, vcc
	v_cmp_lt_u32_e32 vcc, 23, v6
	s_nop 1
	v_addc_co_u32_e32 v7, vcc, v7, v8, vcc
	v_cmp_lt_u32_e32 vcc, 26, v6
	s_nop 1
	v_cndmask_b32_e64 v8, 0, 1, vcc
	v_cmp_lt_u32_e32 vcc, 30, v6
	s_nop 1
	v_addc_co_u32_e32 v7, vcc, v7, v8, vcc
	v_cmp_lt_u32_e32 vcc, 34, v6
	s_nop 1
	v_cndmask_b32_e64 v8, 0, 1, vcc
	v_cmp_lt_u32_e32 vcc, 39, v6
	s_nop 1
	v_addc_co_u32_e32 v7, vcc, v7, v8, vcc
	v_cmp_lt_u32_e32 vcc, 45, v6
	s_nop 1
	v_cndmask_b32_e64 v8, 0, 1, vcc
	v_cmp_lt_u32_e32 vcc, 51, v6
	s_nop 1
	v_addc_co_u32_e32 v7, vcc, v7, v8, vcc
	v_cmp_lt_u32_e32 vcc, 58, v6
	s_nop 1
	v_cndmask_b32_e64 v8, 0, 1, vcc
	v_cmp_lt_u32_e32 vcc, s10, v6
	s_movk_i32 s10, 0x4c
	s_nop 0
	v_addc_co_u32_e32 v7, vcc, v7, v8, vcc
	v_cmp_lt_u32_e32 vcc, s10, v6
	s_movk_i32 s10, 0x56
	s_nop 0
	v_cndmask_b32_e64 v8, 0, 1, vcc
	v_cmp_lt_u32_e32 vcc, s10, v6
	s_movk_i32 s10, 0x62
	s_nop 0
	v_addc_co_u32_e32 v7, vcc, v7, v8, vcc
	v_cmp_lt_u32_e32 vcc, s10, v6
	s_nop 1
	v_cndmask_b32_e64 v8, 0, 1, vcc
	v_cmp_lt_u32_e32 vcc, s57, v6
	s_nop 1
	v_addc_co_u32_e32 v6, vcc, v7, v8, vcc
	v_cmp_lt_i32_e32 vcc, 15, v9
	s_nop 1
	v_cndmask_b32_e32 v6, v9, v6, vcc
	v_lshl_or_b32 v6, v6, 3, v169
	v_ashrrev_i32_e32 v7, 31, v6
	v_lshl_add_u64 v[6:7], v[6:7], 2, s[84:85]
	global_load_dword v16, v[6:7], off
	v_add_u32_e32 v2, 0x300, v4
	v_ashrrev_i32_e32 v6, 3, v2
	v_mov_b32_e32 v9, v6
	v_cmp_lt_u32_e32 vcc, 18, v6
	s_movk_i32 s10, 0x42
	s_nop 0
	v_cndmask_b32_e64 v7, 16, 17, vcc
	v_cmp_lt_u32_e32 vcc, 20, v6
	s_nop 1
	v_cndmask_b32_e64 v8, 0, 1, vcc
	v_cmp_lt_u32_e32 vcc, 23, v6
	s_nop 1
	v_addc_co_u32_e32 v7, vcc, v7, v8, vcc
	v_cmp_lt_u32_e32 vcc, 26, v6
	s_nop 1
	v_cndmask_b32_e64 v8, 0, 1, vcc
	v_cmp_lt_u32_e32 vcc, 30, v6
	s_nop 1
	v_addc_co_u32_e32 v7, vcc, v7, v8, vcc
	v_cmp_lt_u32_e32 vcc, 34, v6
	s_nop 1
	v_cndmask_b32_e64 v8, 0, 1, vcc
	v_cmp_lt_u32_e32 vcc, 39, v6
	s_nop 1
	v_addc_co_u32_e32 v7, vcc, v7, v8, vcc
	v_cmp_lt_u32_e32 vcc, 45, v6
	s_nop 1
	v_cndmask_b32_e64 v8, 0, 1, vcc
	v_cmp_lt_u32_e32 vcc, 51, v6
	s_nop 1
	v_addc_co_u32_e32 v7, vcc, v7, v8, vcc
	v_cmp_lt_u32_e32 vcc, 58, v6
	s_nop 1
	v_cndmask_b32_e64 v8, 0, 1, vcc
	v_cmp_lt_u32_e32 vcc, s10, v6
	s_movk_i32 s10, 0x4c
	s_nop 0
	v_addc_co_u32_e32 v7, vcc, v7, v8, vcc
	v_cmp_lt_u32_e32 vcc, s10, v6
	s_movk_i32 s10, 0x56
	s_nop 0
	v_cndmask_b32_e64 v8, 0, 1, vcc
	v_cmp_lt_u32_e32 vcc, s10, v6
	s_movk_i32 s10, 0x62
	s_nop 0
	v_addc_co_u32_e32 v7, vcc, v7, v8, vcc
	v_cmp_lt_u32_e32 vcc, s10, v6
	s_nop 1
	v_cndmask_b32_e64 v8, 0, 1, vcc
	v_cmp_lt_u32_e32 vcc, s57, v6
	s_nop 1
	v_addc_co_u32_e32 v6, vcc, v7, v8, vcc
	v_cmp_lt_i32_e32 vcc, 15, v9
	s_nop 1
	v_cndmask_b32_e32 v6, v9, v6, vcc
	v_lshl_or_b32 v6, v6, 3, v169
	v_ashrrev_i32_e32 v7, 31, v6
	v_lshl_add_u64 v[6:7], v[6:7], 2, s[84:85]
	global_load_dword v17, v[6:7], off
	s_waitcnt vmcnt(0)
	v_sub_f32_e32 v2, v14, v0
	v_mul_f32_e32 v2, 0x3fb8aa3b, v2
	ds_write_b32 v1, v2
	v_sub_f32_e32 v2, v15, v0
	v_mul_f32_e32 v2, 0x3fb8aa3b, v2
	ds_write_b32 v1, v2 offset:1024
	v_sub_f32_e32 v2, v16, v0
	v_mul_f32_e32 v2, 0x3fb8aa3b, v2
	ds_write_b32 v1, v2 offset:2048
	v_sub_f32_e32 v2, v17, v0
	v_mul_f32_e32 v2, 0x3fb8aa3b, v2
	ds_write_b32 v1, v2 offset:3072
	s_branch .LBB0_209

; DI int opaque_tid() { int t = threadIdx.x; asm volatile("" : "+v"(t)); return t; }
; template <bool MAP>
; DI void transpose_tile(const float* __restrict__ src, int N, int K, int Nvalid, const float* __restrict__ g,
;                        u16* __restrict__ dst, int ldd, int k0, int n0, float* sT) {
;   const int tid = opaque_tid();
;   const int cg = (tid & 15) * 4, kq = tid >> 4;
;   const int sc = MAP ? src_col(n0 + cg) : ((n0 + cg < Nvalid) ? n0 + cg : -1);
; #pragma unroll
;   for (int i = 0; i < 4; ++i) {
;     const int kk = i * 16 + kq;
;     float4 v = make_float4(0.f, 0.f, 0.f, 0.f);
;     if (sc >= 0) {
;       v = *(const float4*)(src + (size_t)(k0 + kk) * N + sc);
;       if (g) { const float gg = g[k0 + kk]; v.x *= gg; v.y *= gg; v.z *= gg; v.w *= gg; }
;     }
;     float* d = sT + kk * 65 + cg;
;     d[0] = v.x; d[1] = v.y; d[2] = v.z; d[3] = v.w;
;   }
.LBB0_1534:
	s_or_b64 exec, exec, s[0:1]
	s_and_b32 s16, s15, 0x3c0
	v_ashrrev_i32_e32 v0, 4, v14
	v_cmp_lt_i32_e64 s[44:45], -1, v2
	v_lshl_add_u64 v[10:11], v[2:3], 2, s[66:67]
	v_mov_b32_e32 v96, 0
	v_mov_b32_e32 v97, 0
	v_mov_b32_e32 v98, 0
	v_mov_b32_e32 v99, 0
	v_mov_b32_e32 v100, 0
	v_mov_b32_e32 v101, 0
	v_mov_b32_e32 v102, 0
	v_mov_b32_e32 v103, 0
	v_mov_b32_e32 v104, 0
	v_mov_b32_e32 v105, 0
	v_mov_b32_e32 v106, 0
	v_mov_b32_e32 v107, 0
	v_mov_b32_e32 v108, 0
	v_mov_b32_e32 v109, 0
	v_mov_b32_e32 v110, 0
	v_mov_b32_e32 v111, 0
	v_mov_b32_e32 v116, 1.0
	v_mov_b32_e32 v117, 1.0
	v_mov_b32_e32 v118, 1.0
	v_mov_b32_e32 v119, 1.0
	v_lshlrev_b32_e32 v1, 2, v1
	s_movk_i32 s0, 0x104
	v_mul_lo_u32 v2, v0, s0
	v_add_u32_e32 v2, v1, v2
	s_and_saveexec_b64 s[0:1], s[44:45]
	s_cbranch_execz .Lcvin0_skip
	v_add_u32_e32 v12, s16, v0
	s_movk_i32 s6, 0x7520
	v_mad_i64_i32 v[120:121], s[6:7], v12, s6, v[10:11]
	global_load_dwordx4 v[96:99], v[120:121], off
	v_add_u32_e32 v13, 16, v12
	s_movk_i32 s6, 0x7520
	v_mad_i64_i32 v[120:121], s[6:7], v13, s6, v[10:11]
	global_load_dwordx4 v[100:103], v[120:121], off
	v_add_u32_e32 v13, 32, v12
	s_movk_i32 s6, 0x7520
	v_mad_i64_i32 v[120:121], s[6:7], v13, s6, v[10:11]
	global_load_dwordx4 v[104:107], v[120:121], off
	v_add_u32_e32 v13, 48, v12
	s_movk_i32 s6, 0x7520
	v_mad_i64_i32 v[120:121], s[6:7], v13, s6, v[10:11]
	global_load_dwordx4 v[108:111], v[120:121], off
	s_andn2_b64 vcc, exec, s[58:59]
	s_cbranch_vccnz .Lcvin0_skip
	v_ashrrev_i32_e32 v13, 31, v12
	v_lshl_add_u64 v[12:13], v[12:13], 2, s[64:65]
	global_load_dword v116, v[12:13], off
	global_load_dword v117, v[12:13], off offset:64
	global_load_dword v118, v[12:13], off offset:128
	global_load_dword v119, v[12:13], off offset:192
.Lcvin0_skip:
	s_or_b64 exec, exec, s[0:1]
	s_waitcnt vmcnt(0)
	v_mul_f32_e32 v96, v96, v116
	v_mul_f32_e32 v97, v97, v116
	v_mul_f32_e32 v98, v98, v116
	v_mul_f32_e32 v99, v99, v116
	v_mul_f32_e32 v100, v100, v117
	v_mul_f32_e32 v101, v101, v117
	v_mul_f32_e32 v102, v102, v117
	v_mul_f32_e32 v103, v103, v117
	v_mul_f32_e32 v104, v104, v118
	v_mul_f32_e32 v105, v105, v118
	v_mul_f32_e32 v106, v106, v118
	v_mul_f32_e32 v107, v107, v118
	v_mul_f32_e32 v108, v108, v119
	v_mul_f32_e32 v109, v109, v119
	v_mul_f32_e32 v110, v110, v119
	v_mul_f32_e32 v111, v111, v119
	ds_write2_b32 v2, v96, v97 offset1:1
	ds_write2_b32 v2, v98, v99 offset0:2 offset1:3
	v_add_u32_e32 v1, 0x1040, v2
	ds_write2_b32 v1, v100, v101 offset1:1
	v_add_u32_e32 v1, 0x1048, v2
	ds_write2_b32 v1, v102, v103 offset1:1
	v_add_u32_e32 v1, 0x2080, v2
	ds_write2_b32 v1, v104, v105 offset1:1
	v_add_u32_e32 v1, 0x2088, v2
	ds_write2_b32 v1, v106, v107 offset1:1
	v_mov_b32_e32 v4, v108
	v_mov_b32_e32 v5, v109
	v_mov_b32_e32 v6, v110
	v_mov_b32_e32 v7, v111
	s_branch .LBB0_1487
